# GEMM: the three MFMA-phase LDS-DMA issues moved to just after MFMA 2,6,10 (early in the phase, away from the partner wave's own DMA burst); attention loops and address hoist unchanged from previous be
# speedup vs baseline: 1.0300x; 1.0095x over previous
; #define STAGE_ALL(bufi, kt) do { STAGEA(SA(bufi, 0), brow, kt); STAGEA(SA(bufi, 1), brow + HALF, kt); STAGEB(SB(bufi), bcol, kt); } while (0)
; #define WAIT_V(n) asm volatile("s_waitcnt vmcnt(" #n ")" ::: "memory")
; #define BAR __builtin_amdgcn_s_barrier()
;     ...
;     for (int t = 0; t < nt; ++t) {
;       const char* pa = (const char*)SA(b, wr >> 1);
;       const char* pb = (const char*)SB(b);
;       bf16x8 At[4][2], Bf[4][2];
; #pragma unroll
;       for (int m = 0; m < 4; ++m)
; #pragma unroll
;         for (int k = 0; k < 2; ++k) At[m][k] = *reinterpret_cast<const bf16x8*>(pa + lds_byte((wr & 1) * 64 + m * 16 + fr, k * 32 + fq * 8));
; #pragma unroll
;       for (int n = 0; n < 4; ++n)
; #pragma unroll
;         for (int k = 0; k < 2; ++k) Bf[n][k] = *reinterpret_cast<const bf16x8*>(pb + lds_byte(wc * 64 + n * 16 + fr, k * 32 + fq * 8));
;       if (t + 2 < nt) { const int b2 = (b == 0) ? 2 : b - 1; STAGE_ALL(b2, t + 2); WAIT_V(6); } else { WAIT_V(0); }
;       asm volatile("s_waitcnt lgkmcnt(0)" ::: "memory");
;       __builtin_amdgcn_sched_barrier(0);
;       BAR;
;       __builtin_amdgcn_sched_barrier(0);
;       __builtin_amdgcn_s_setprio(1);
; #pragma unroll
;       for (int k = 0; k < 2; ++k)
; #pragma unroll
;         for (int m = 0; m < 4; ++m)
; #pragma unroll
;           for (int n = 0; n < 4; ++n) acc[m][n] = __builtin_amdgcn_mfma_f32_16x16x32_bf16(Bf[n][k], At[m][k], acc[m][n], 0, 0, 0);
;       __builtin_amdgcn_s_setprio(0);
;       __builtin_amdgcn_sched_barrier(0);
;       BAR;
;       __builtin_amdgcn_sched_barrier(0);
;       b = (b == 2) ? 0 : b + 1;
;     }
.LBB0_41:
	s_waitcnt lgkmcnt(0)
	s_barrier
	s_setprio 1
	s_waitcnt lgkmcnt(0)
	v_mfma_f32_16x16x32_bf16 v[60:63], v[112:115], v[108:111], v[60:63]
	v_mfma_f32_16x16x32_bf16 v[56:59], v[116:119], v[108:111], v[56:59]
	s_cmp_gt_u32 s62, 41
	s_cbranch_scc1 .Lgc1_skd3
	s_add_u32 m0, s98, 0x6000
	s_nop 0
	global_load_lds_dwordx4 v[168:169], off
.Lgc1_skd3:
	v_mfma_f32_16x16x32_bf16 v[52:55], v[120:123], v[108:111], v[52:55]
	v_mfma_f32_16x16x32_bf16 v[48:51], v[124:127], v[108:111], v[48:51]
	v_mfma_f32_16x16x32_bf16 v[44:47], v[112:115], v[104:107], v[44:47]
	v_mfma_f32_16x16x32_bf16 v[40:43], v[116:119], v[104:107], v[40:43]
	s_cmp_gt_u32 s62, 41
	s_cbranch_scc1 .Lgc1_skd4
	s_add_u32 m0, s98, 0x8000
	s_nop 0
	global_load_lds_dwordx4 v[170:171], off
.Lgc1_skd4:
	v_mfma_f32_16x16x32_bf16 v[36:39], v[120:123], v[104:107], v[36:39]
	v_mfma_f32_16x16x32_bf16 v[32:35], v[124:127], v[104:107], v[32:35]
	v_mfma_f32_16x16x32_bf16 v[28:31], v[112:115], v[100:103], v[28:31]
	v_mfma_f32_16x16x32_bf16 v[24:27], v[116:119], v[100:103], v[24:27]
	s_cmp_gt_u32 s62, 41
	s_cbranch_scc1 .Lgc1_skd5
	s_add_u32 m0, s98, 0xa000
	s_nop 0
	global_load_lds_dwordx4 v[172:173], off
.Lgc1_skd5:
	v_mfma_f32_16x16x32_bf16 v[20:23], v[120:123], v[100:103], v[20:23]
	v_mfma_f32_16x16x32_bf16 v[16:19], v[124:127], v[100:103], v[16:19]
	v_mfma_f32_16x16x32_bf16 v[12:15], v[112:115], v[96:99], v[12:15]
	v_mfma_f32_16x16x32_bf16 v[8:11], v[116:119], v[96:99], v[8:11]
	v_mfma_f32_16x16x32_bf16 v[4:7], v[120:123], v[96:99], v[4:7]
	v_mfma_f32_16x16x32_bf16 v[0:3], v[124:127], v[96:99], v[0:3]
	v_mfma_f32_16x16x32_bf16 v[60:63], v[80:83], v[76:79], v[60:63]
	v_mfma_f32_16x16x32_bf16 v[56:59], v[84:87], v[76:79], v[56:59]
	v_mfma_f32_16x16x32_bf16 v[52:55], v[88:91], v[76:79], v[52:55]
	v_mfma_f32_16x16x32_bf16 v[48:51], v[92:95], v[76:79], v[48:51]
	v_mfma_f32_16x16x32_bf16 v[44:47], v[80:83], v[72:75], v[44:47]
	v_mfma_f32_16x16x32_bf16 v[40:43], v[84:87], v[72:75], v[40:43]
	v_mfma_f32_16x16x32_bf16 v[36:39], v[88:91], v[72:75], v[36:39]
	v_mfma_f32_16x16x32_bf16 v[32:35], v[92:95], v[72:75], v[32:35]
	v_mfma_f32_16x16x32_bf16 v[28:31], v[80:83], v[68:71], v[28:31]
	v_mfma_f32_16x16x32_bf16 v[24:27], v[84:87], v[68:71], v[24:27]
	v_mfma_f32_16x16x32_bf16 v[20:23], v[88:91], v[68:71], v[20:23]
	v_mfma_f32_16x16x32_bf16 v[16:19], v[92:95], v[68:71], v[16:19]
	v_mfma_f32_16x16x32_bf16 v[12:15], v[80:83], v[64:67], v[12:15]
	v_mfma_f32_16x16x32_bf16 v[8:11], v[84:87], v[64:67], v[8:11]
	v_mfma_f32_16x16x32_bf16 v[4:7], v[88:91], v[64:67], v[4:7]
	v_mfma_f32_16x16x32_bf16 v[0:3], v[92:95], v[64:67], v[0:3]
	s_setprio 0
	s_add_i32 s36, s61, 1
	s_cmp_lg_u32 s61, 2
	s_cselect_b32 s61, s36, 0
	s_add_i32 s62, s62, 1
	s_add_u32 s10, s10, 0x80
	s_addc_u32 s11, s11, 0
	s_mul_i32 s36, s61, 0xc000
	v_add_u32_e32 v160, s36, v174
	v_add_u32_e32 v161, s36, v131
	s_mul_i32 s36, s61, 0x6000
	s_addk_i32 s36, 0xa000
	s_cmp_lg_u32 s61, 0
	s_cselect_b32 s36, s36, 0xc000
	s_lshl_b32 s36, s36, 1
	s_add_u32 s98, s36, s99
	v_lshl_add_u64 v[162:163], v[162:163], 0, s[14:15]
	v_lshl_add_u64 v[164:165], v[164:165], 0, s[14:15]
	v_lshl_add_u64 v[166:167], v[166:167], 0, s[14:15]
	v_lshl_add_u64 v[168:169], v[168:169], 0, s[14:15]
	v_lshl_add_u64 v[170:171], v[170:171], 0, s[14:15]
	v_lshl_add_u64 v[172:173], v[172:173], 0, s[14:15]
	s_barrier
	s_cmpk_eq_i32 s10, 0x1600
	s_cbranch_scc1 .LBB0_46

; #define STAGE_ALL(bufi, kt) do { STAGEA(SA(bufi, 0), brow, kt); STAGEA(SA(bufi, 1), brow + HALF, kt); STAGEB(SB(bufi), bcol, kt); } while (0)
; #define WAIT_V(n) asm volatile("s_waitcnt vmcnt(" #n ")" ::: "memory")
; #define BAR __builtin_amdgcn_s_barrier()
;     ...
;     for (int t = 0; t < nt; ++t) {
;       const char* pa = (const char*)SA(b, wr >> 1);
;       const char* pb = (const char*)SB(b);
;       bf16x8 At[4][2], Bf[4][2];
; #pragma unroll
;       for (int m = 0; m < 4; ++m)
; #pragma unroll
;         for (int k = 0; k < 2; ++k) At[m][k] = *reinterpret_cast<const bf16x8*>(pa + lds_byte((wr & 1) * 64 + m * 16 + fr, k * 32 + fq * 8));
; #pragma unroll
;       for (int n = 0; n < 4; ++n)
; #pragma unroll
;         for (int k = 0; k < 2; ++k) Bf[n][k] = *reinterpret_cast<const bf16x8*>(pb + lds_byte(wc * 64 + n * 16 + fr, k * 32 + fq * 8));
;       if (t + 2 < nt) { const int b2 = (b == 0) ? 2 : b - 1; STAGE_ALL(b2, t + 2); WAIT_V(6); } else { WAIT_V(0); }
;       asm volatile("s_waitcnt lgkmcnt(0)" ::: "memory");
;       __builtin_amdgcn_sched_barrier(0);
;       BAR;
;       __builtin_amdgcn_sched_barrier(0);
;       __builtin_amdgcn_s_setprio(1);
; #pragma unroll
;       for (int k = 0; k < 2; ++k)
; #pragma unroll
;         for (int m = 0; m < 4; ++m)
; #pragma unroll
;           for (int n = 0; n < 4; ++n) acc[m][n] = __builtin_amdgcn_mfma_f32_16x16x32_bf16(Bf[n][k], At[m][k], acc[m][n], 0, 0, 0);
;       __builtin_amdgcn_s_setprio(0);
;       __builtin_amdgcn_sched_barrier(0);
;       BAR;
;       __builtin_amdgcn_sched_barrier(0);
;       b = (b == 2) ? 0 : b + 1;
;     }
.LBB0_73:
	s_waitcnt lgkmcnt(0)
	s_barrier
	s_setprio 1
	s_waitcnt lgkmcnt(0)
	v_mfma_f32_16x16x32_bf16 v[56:59], v[112:115], v[108:111], v[56:59]
	v_mfma_f32_16x16x32_bf16 v[48:51], v[116:119], v[108:111], v[48:51]
	s_cmp_gt_u32 s64, 13
	s_cbranch_scc1 .Lgc2_skd3
	s_add_u32 m0, s98, 0x6000
	s_nop 0
	global_load_lds_dwordx4 v[168:169], off
.Lgc2_skd3:
	v_mfma_f32_16x16x32_bf16 v[60:63], v[120:123], v[108:111], v[60:63]
	v_mfma_f32_16x16x32_bf16 v[52:55], v[124:127], v[108:111], v[52:55]
	v_mfma_f32_16x16x32_bf16 v[40:43], v[112:115], v[104:107], v[40:43]
	v_mfma_f32_16x16x32_bf16 v[32:35], v[116:119], v[104:107], v[32:35]
	s_cmp_gt_u32 s64, 13
	s_cbranch_scc1 .Lgc2_skd4
	s_add_u32 m0, s98, 0x8000
	s_nop 0
	global_load_lds_dwordx4 v[170:171], off
.Lgc2_skd4:
	v_mfma_f32_16x16x32_bf16 v[44:47], v[120:123], v[104:107], v[44:47]
	v_mfma_f32_16x16x32_bf16 v[36:39], v[124:127], v[104:107], v[36:39]
	v_mfma_f32_16x16x32_bf16 v[24:27], v[112:115], v[100:103], v[24:27]
	v_mfma_f32_16x16x32_bf16 v[16:19], v[116:119], v[100:103], v[16:19]
	s_cmp_gt_u32 s64, 13
	s_cbranch_scc1 .Lgc2_skd5
	s_add_u32 m0, s98, 0xa000
	s_nop 0
	global_load_lds_dwordx4 v[172:173], off
.Lgc2_skd5:
	v_mfma_f32_16x16x32_bf16 v[28:31], v[120:123], v[100:103], v[28:31]
	v_mfma_f32_16x16x32_bf16 v[20:23], v[124:127], v[100:103], v[20:23]
	v_mfma_f32_16x16x32_bf16 v[8:11], v[112:115], v[96:99], v[8:11]
	v_mfma_f32_16x16x32_bf16 v[0:3], v[116:119], v[96:99], v[0:3]
	v_mfma_f32_16x16x32_bf16 v[12:15], v[120:123], v[96:99], v[12:15]
	v_mfma_f32_16x16x32_bf16 v[4:7], v[124:127], v[96:99], v[4:7]
	v_mfma_f32_16x16x32_bf16 v[56:59], v[80:83], v[76:79], v[56:59]
	v_mfma_f32_16x16x32_bf16 v[48:51], v[84:87], v[76:79], v[48:51]
	v_mfma_f32_16x16x32_bf16 v[60:63], v[88:91], v[76:79], v[60:63]
	v_mfma_f32_16x16x32_bf16 v[52:55], v[92:95], v[76:79], v[52:55]
	v_mfma_f32_16x16x32_bf16 v[40:43], v[80:83], v[72:75], v[40:43]
	v_mfma_f32_16x16x32_bf16 v[32:35], v[84:87], v[72:75], v[32:35]
	v_mfma_f32_16x16x32_bf16 v[44:47], v[88:91], v[72:75], v[44:47]
	v_mfma_f32_16x16x32_bf16 v[36:39], v[92:95], v[72:75], v[36:39]
	v_mfma_f32_16x16x32_bf16 v[24:27], v[80:83], v[68:71], v[24:27]
	v_mfma_f32_16x16x32_bf16 v[16:19], v[84:87], v[68:71], v[16:19]
	v_mfma_f32_16x16x32_bf16 v[28:31], v[88:91], v[68:71], v[28:31]
	v_mfma_f32_16x16x32_bf16 v[20:23], v[92:95], v[68:71], v[20:23]
	v_mfma_f32_16x16x32_bf16 v[8:11], v[80:83], v[64:67], v[8:11]
	v_mfma_f32_16x16x32_bf16 v[0:3], v[84:87], v[64:67], v[0:3]
	v_mfma_f32_16x16x32_bf16 v[12:15], v[88:91], v[64:67], v[12:15]
	v_mfma_f32_16x16x32_bf16 v[4:7], v[92:95], v[64:67], v[4:7]
	s_setprio 0
	s_add_i32 s36, s43, 1
	s_cmp_lg_u32 s43, 2
	s_cselect_b32 s43, s36, 0
	s_add_i32 s64, s64, 1
	s_add_u32 s10, s10, 0x80
	s_addc_u32 s11, s11, 0
	s_mul_i32 s36, s43, 0xc000
	v_add_u32_e32 v160, s36, v174
	v_add_u32_e32 v161, s36, v131
	s_mul_i32 s36, s43, 0x6000
	s_addk_i32 s36, 0xa000
	s_cmp_lg_u32 s43, 0
	s_cselect_b32 s36, s36, 0xc000
	s_lshl_b32 s36, s36, 1
	s_add_u32 s98, s36, s99
	v_lshl_add_u64 v[162:163], v[162:163], 0, s[14:15]
	v_lshl_add_u64 v[164:165], v[164:165], 0, s[14:15]
	v_lshl_add_u64 v[166:167], v[166:167], 0, s[14:15]
	v_lshl_add_u64 v[168:169], v[168:169], 0, s[14:15]
	v_lshl_add_u64 v[170:171], v[170:171], 0, s[14:15]
	v_lshl_add_u64 v[172:173], v[172:173], 0, s[14:15]
	s_barrier
	s_cmpk_eq_i32 s10, 0x800
	s_cbranch_scc1 .LBB0_78

; #define STAGE_ALL(bufi, kt) do { STAGEA(SA(bufi, 0), brow, kt); STAGEA(SA(bufi, 1), brow + HALF, kt); STAGEB(SB(bufi), bcol, kt); } while (0)
; #define WAIT_V(n) asm volatile("s_waitcnt vmcnt(" #n ")" ::: "memory")
; #define BAR __builtin_amdgcn_s_barrier()
;     ...
;     for (int t = 0; t < nt; ++t) {
;       const char* pa = (const char*)SA(b, wr >> 1);
;       const char* pb = (const char*)SB(b);
;       bf16x8 At[4][2], Bf[4][2];
; #pragma unroll
;       for (int m = 0; m < 4; ++m)
; #pragma unroll
;         for (int k = 0; k < 2; ++k) At[m][k] = *reinterpret_cast<const bf16x8*>(pa + lds_byte((wr & 1) * 64 + m * 16 + fr, k * 32 + fq * 8));
; #pragma unroll
;       for (int n = 0; n < 4; ++n)
; #pragma unroll
;         for (int k = 0; k < 2; ++k) Bf[n][k] = *reinterpret_cast<const bf16x8*>(pb + lds_byte(wc * 64 + n * 16 + fr, k * 32 + fq * 8));
;       if (t + 2 < nt) { const int b2 = (b == 0) ? 2 : b - 1; STAGE_ALL(b2, t + 2); WAIT_V(6); } else { WAIT_V(0); }
;       asm volatile("s_waitcnt lgkmcnt(0)" ::: "memory");
;       __builtin_amdgcn_sched_barrier(0);
;       BAR;
;       __builtin_amdgcn_sched_barrier(0);
;       __builtin_amdgcn_s_setprio(1);
; #pragma unroll
;       for (int k = 0; k < 2; ++k)
; #pragma unroll
;         for (int m = 0; m < 4; ++m)
; #pragma unroll
;           for (int n = 0; n < 4; ++n) acc[m][n] = __builtin_amdgcn_mfma_f32_16x16x32_bf16(Bf[n][k], At[m][k], acc[m][n], 0, 0, 0);
;       __builtin_amdgcn_s_setprio(0);
;       __builtin_amdgcn_sched_barrier(0);
;       BAR;
;       __builtin_amdgcn_sched_barrier(0);
;       b = (b == 2) ? 0 : b + 1;
;     }
.LBB0_108:
	s_waitcnt lgkmcnt(0)
	s_barrier
	s_setprio 1
	s_waitcnt lgkmcnt(0)
	v_mfma_f32_16x16x32_bf16 v[60:63], v[112:115], v[108:111], v[60:63]
	v_mfma_f32_16x16x32_bf16 v[56:59], v[116:119], v[108:111], v[56:59]
	s_cmp_gt_u32 s41, 13
	s_cbranch_scc1 .Lgc3_skd3
	s_add_u32 m0, s98, 0x6000
	s_nop 0
	global_load_lds_dwordx4 v[168:169], off
.Lgc3_skd3:
	v_mfma_f32_16x16x32_bf16 v[52:55], v[120:123], v[108:111], v[52:55]
	v_mfma_f32_16x16x32_bf16 v[48:51], v[124:127], v[108:111], v[48:51]
	v_mfma_f32_16x16x32_bf16 v[44:47], v[112:115], v[104:107], v[44:47]
	v_mfma_f32_16x16x32_bf16 v[40:43], v[116:119], v[104:107], v[40:43]
	s_cmp_gt_u32 s41, 13
	s_cbranch_scc1 .Lgc3_skd4
	s_add_u32 m0, s98, 0x8000
	s_nop 0
	global_load_lds_dwordx4 v[170:171], off
.Lgc3_skd4:
	v_mfma_f32_16x16x32_bf16 v[36:39], v[120:123], v[104:107], v[36:39]
	v_mfma_f32_16x16x32_bf16 v[32:35], v[124:127], v[104:107], v[32:35]
	v_mfma_f32_16x16x32_bf16 v[28:31], v[112:115], v[100:103], v[28:31]
	v_mfma_f32_16x16x32_bf16 v[24:27], v[116:119], v[100:103], v[24:27]
	s_cmp_gt_u32 s41, 13
	s_cbranch_scc1 .Lgc3_skd5
	s_add_u32 m0, s98, 0xa000
	s_nop 0
	global_load_lds_dwordx4 v[172:173], off
.Lgc3_skd5:
	v_mfma_f32_16x16x32_bf16 v[20:23], v[120:123], v[100:103], v[20:23]
	v_mfma_f32_16x16x32_bf16 v[16:19], v[124:127], v[100:103], v[16:19]
	v_mfma_f32_16x16x32_bf16 v[12:15], v[112:115], v[96:99], v[12:15]
	v_mfma_f32_16x16x32_bf16 v[8:11], v[116:119], v[96:99], v[8:11]
	v_mfma_f32_16x16x32_bf16 v[4:7], v[120:123], v[96:99], v[4:7]
	v_mfma_f32_16x16x32_bf16 v[0:3], v[124:127], v[96:99], v[0:3]
	v_mfma_f32_16x16x32_bf16 v[60:63], v[80:83], v[76:79], v[60:63]
	v_mfma_f32_16x16x32_bf16 v[56:59], v[84:87], v[76:79], v[56:59]
	v_mfma_f32_16x16x32_bf16 v[52:55], v[88:91], v[76:79], v[52:55]
	v_mfma_f32_16x16x32_bf16 v[48:51], v[92:95], v[76:79], v[48:51]
	v_mfma_f32_16x16x32_bf16 v[44:47], v[80:83], v[72:75], v[44:47]
	v_mfma_f32_16x16x32_bf16 v[40:43], v[84:87], v[72:75], v[40:43]
	v_mfma_f32_16x16x32_bf16 v[36:39], v[88:91], v[72:75], v[36:39]
	v_mfma_f32_16x16x32_bf16 v[32:35], v[92:95], v[72:75], v[32:35]
	v_mfma_f32_16x16x32_bf16 v[28:31], v[80:83], v[68:71], v[28:31]
	v_mfma_f32_16x16x32_bf16 v[24:27], v[84:87], v[68:71], v[24:27]
	v_mfma_f32_16x16x32_bf16 v[20:23], v[88:91], v[68:71], v[20:23]
	v_mfma_f32_16x16x32_bf16 v[16:19], v[92:95], v[68:71], v[16:19]
	v_mfma_f32_16x16x32_bf16 v[12:15], v[80:83], v[64:67], v[12:15]
	v_mfma_f32_16x16x32_bf16 v[8:11], v[84:87], v[64:67], v[8:11]
	v_mfma_f32_16x16x32_bf16 v[4:7], v[88:91], v[64:67], v[4:7]
	v_mfma_f32_16x16x32_bf16 v[0:3], v[92:95], v[64:67], v[0:3]
	s_setprio 0
	s_add_i32 s36, s39, 1
	s_cmp_lg_u32 s39, 2
	s_cselect_b32 s39, s36, 0
	s_add_i32 s41, s41, 1
	s_add_u32 s10, s10, 0x80
	s_addc_u32 s11, s11, 0
	s_mul_i32 s36, s39, 0xc000
	v_add_u32_e32 v160, s36, v174
	v_add_u32_e32 v161, s36, v131
	s_mul_i32 s36, s39, 0x6000
	s_addk_i32 s36, 0xa000
	s_cmp_lg_u32 s39, 0
	s_cselect_b32 s36, s36, 0xc000
	s_lshl_b32 s36, s36, 1
	s_add_u32 s98, s36, s99
	v_lshl_add_u64 v[162:163], v[162:163], 0, s[14:15]
	v_lshl_add_u64 v[164:165], v[164:165], 0, s[14:15]
	v_lshl_add_u64 v[166:167], v[166:167], 0, s[14:15]
	v_lshl_add_u64 v[168:169], v[168:169], 0, s[14:15]
	v_lshl_add_u64 v[170:171], v[170:171], 0, s[14:15]
	v_lshl_add_u64 v[172:173], v[172:173], 0, s[14:15]
	s_barrier
	s_cmpk_eq_i32 s10, 0x800
	s_cbranch_scc1 .LBB0_113

;     ...
;       __builtin_amdgcn_s_setprio(1);
; #pragma unroll
;       for (int k = 0; k < 2; ++k)
; #pragma unroll
;         for (int m = 0; m < 4; ++m)
; #pragma unroll
;           for (int n = 0; n < 4; ++n) acc[m][n] = __builtin_amdgcn_mfma_f32_16x16x32_bf16(Bf[n][k], At[m][k], acc[m][n], 0, 0, 0);
.LBB0_1021:
	s_waitcnt lgkmcnt(0)
	s_barrier
	s_setprio 1
	s_waitcnt lgkmcnt(0)
	v_mfma_f32_16x16x32_bf16 v[56:59], v[112:115], v[108:111], v[56:59]
	v_mfma_f32_16x16x32_bf16 v[60:63], v[116:119], v[108:111], v[60:63]
	s_cmp_gt_u32 s41, 13
	s_cbranch_scc1 .Lgc4_skd3
	s_add_u32 m0, s98, 0x6000
	s_nop 0
	global_load_lds_dwordx4 v[168:169], off

; #define BAR __builtin_amdgcn_s_barrier()
;     ...
;       __builtin_amdgcn_s_setprio(1);
; #pragma unroll
;       for (int k = 0; k < 2; ++k)
; #pragma unroll
;         for (int m = 0; m < 4; ++m)
; #pragma unroll
;           for (int n = 0; n < 4; ++n) acc[m][n] = __builtin_amdgcn_mfma_f32_16x16x32_bf16(Bf[n][k], At[m][k], acc[m][n], 0, 0, 0);
;       __builtin_amdgcn_s_setprio(0);
;       __builtin_amdgcn_sched_barrier(0);
;       BAR;
;       __builtin_amdgcn_sched_barrier(0);
;       b = (b == 2) ? 0 : b + 1;
;     }
.Lgc4_skd5:
	v_mfma_f32_16x16x32_bf16 v[20:23], v[120:123], v[100:103], v[20:23]
	v_mfma_f32_16x16x32_bf16 v[16:19], v[124:127], v[100:103], v[16:19]
	v_mfma_f32_16x16x32_bf16 v[12:15], v[112:115], v[96:99], v[12:15]
	v_mfma_f32_16x16x32_bf16 v[8:11], v[116:119], v[96:99], v[8:11]
	v_mfma_f32_16x16x32_bf16 v[4:7], v[120:123], v[96:99], v[4:7]
	v_mfma_f32_16x16x32_bf16 v[0:3], v[124:127], v[96:99], v[0:3]
	v_mfma_f32_16x16x32_bf16 v[56:59], v[80:83], v[76:79], v[56:59]
	v_mfma_f32_16x16x32_bf16 v[60:63], v[84:87], v[76:79], v[60:63]
	v_mfma_f32_16x16x32_bf16 v[52:55], v[88:91], v[76:79], v[52:55]
	v_mfma_f32_16x16x32_bf16 v[48:51], v[92:95], v[76:79], v[48:51]
	v_mfma_f32_16x16x32_bf16 v[44:47], v[80:83], v[72:75], v[44:47]
	v_mfma_f32_16x16x32_bf16 v[40:43], v[84:87], v[72:75], v[40:43]
	v_mfma_f32_16x16x32_bf16 v[36:39], v[88:91], v[72:75], v[36:39]
	v_mfma_f32_16x16x32_bf16 v[32:35], v[92:95], v[72:75], v[32:35]
	v_mfma_f32_16x16x32_bf16 v[28:31], v[80:83], v[68:71], v[28:31]
	v_mfma_f32_16x16x32_bf16 v[24:27], v[84:87], v[68:71], v[24:27]
	v_mfma_f32_16x16x32_bf16 v[20:23], v[88:91], v[68:71], v[20:23]
	v_mfma_f32_16x16x32_bf16 v[16:19], v[92:95], v[68:71], v[16:19]
	v_mfma_f32_16x16x32_bf16 v[12:15], v[80:83], v[64:67], v[12:15]
	v_mfma_f32_16x16x32_bf16 v[8:11], v[84:87], v[64:67], v[8:11]
	v_mfma_f32_16x16x32_bf16 v[4:7], v[88:91], v[64:67], v[4:7]
	v_mfma_f32_16x16x32_bf16 v[0:3], v[92:95], v[64:67], v[0:3]
	s_setprio 0
	s_add_i32 s36, s39, 1
	s_cmp_lg_u32 s39, 2
	s_cselect_b32 s39, s36, 0
	s_add_i32 s41, s41, 1
	s_add_u32 s10, s10, 0x80
	s_addc_u32 s11, s11, 0
	s_mul_i32 s36, s39, 0xc000
	v_add_u32_e32 v160, s36, v174
	v_add_u32_e32 v161, s36, v131
	s_mul_i32 s36, s39, 0x6000
	s_addk_i32 s36, 0xa000
	s_cmp_lg_u32 s39, 0
	s_cselect_b32 s36, s36, 0xc000
	s_lshl_b32 s36, s36, 1
	s_add_u32 s98, s36, s99
	v_lshl_add_u64 v[162:163], v[162:163], 0, s[14:15]
	v_lshl_add_u64 v[164:165], v[164:165], 0, s[14:15]
	v_lshl_add_u64 v[166:167], v[166:167], 0, s[14:15]
	v_lshl_add_u64 v[168:169], v[168:169], 0, s[14:15]
	v_lshl_add_u64 v[170:171], v[170:171], 0, s[14:15]
	v_lshl_add_u64 v[172:173], v[172:173], 0, s[14:15]
	s_barrier
	s_cmpk_eq_i32 s10, 0x800
	s_cbranch_scc1 .LBB0_1026

; #define STAGE_ALL(bufi, kt) do { STAGEA(SA(bufi, 0), brow, kt); STAGEA(SA(bufi, 1), brow + HALF, kt); STAGEB(SB(bufi), bcol, kt); } while (0)
; #define WAIT_V(n) asm volatile("s_waitcnt vmcnt(" #n ")" ::: "memory")
; #define BAR __builtin_amdgcn_s_barrier()
;     ...
;     for (int t = 0; t < nt; ++t) {
;       const char* pa = (const char*)SA(b, wr >> 1);
;       const char* pb = (const char*)SB(b);
;       bf16x8 At[4][2], Bf[4][2];
; #pragma unroll
;       for (int m = 0; m < 4; ++m)
; #pragma unroll
;         for (int k = 0; k < 2; ++k) At[m][k] = *reinterpret_cast<const bf16x8*>(pa + lds_byte((wr & 1) * 64 + m * 16 + fr, k * 32 + fq * 8));
; #pragma unroll
;       for (int n = 0; n < 4; ++n)
; #pragma unroll
;         for (int k = 0; k < 2; ++k) Bf[n][k] = *reinterpret_cast<const bf16x8*>(pb + lds_byte(wc * 64 + n * 16 + fr, k * 32 + fq * 8));
;       if (t + 2 < nt) { const int b2 = (b == 0) ? 2 : b - 1; STAGE_ALL(b2, t + 2); WAIT_V(6); } else { WAIT_V(0); }
;       asm volatile("s_waitcnt lgkmcnt(0)" ::: "memory");
;       __builtin_amdgcn_sched_barrier(0);
;       BAR;
;       __builtin_amdgcn_sched_barrier(0);
;       __builtin_amdgcn_s_setprio(1);
; #pragma unroll
;       for (int k = 0; k < 2; ++k)
; #pragma unroll
;         for (int m = 0; m < 4; ++m)
; #pragma unroll
;           for (int n = 0; n < 4; ++n) acc[m][n] = __builtin_amdgcn_mfma_f32_16x16x32_bf16(Bf[n][k], At[m][k], acc[m][n], 0, 0, 0);
;       __builtin_amdgcn_s_setprio(0);
;       __builtin_amdgcn_sched_barrier(0);
;       BAR;
;       __builtin_amdgcn_sched_barrier(0);
;       b = (b == 2) ? 0 : b + 1;
;     }
.LBB0_1057:
	s_waitcnt lgkmcnt(0)
	s_barrier
	s_setprio 1
	s_waitcnt lgkmcnt(0)
	v_mfma_f32_16x16x32_bf16 v[60:63], v[112:115], v[108:111], v[60:63]
	v_mfma_f32_16x16x32_bf16 v[56:59], v[116:119], v[108:111], v[56:59]
	s_cmp_gt_u32 s61, 41
	s_cbranch_scc1 .Lgc5_skd3
	s_add_u32 m0, s98, 0x6000
	s_nop 0
	global_load_lds_dwordx4 v[168:169], off
.Lgc5_skd3:
	v_mfma_f32_16x16x32_bf16 v[52:55], v[120:123], v[108:111], v[52:55]
	v_mfma_f32_16x16x32_bf16 v[48:51], v[124:127], v[108:111], v[48:51]
	v_mfma_f32_16x16x32_bf16 v[44:47], v[112:115], v[104:107], v[44:47]
	v_mfma_f32_16x16x32_bf16 v[40:43], v[116:119], v[104:107], v[40:43]
	s_cmp_gt_u32 s61, 41
	s_cbranch_scc1 .Lgc5_skd4
	s_add_u32 m0, s98, 0x8000
	s_nop 0
	global_load_lds_dwordx4 v[170:171], off
.Lgc5_skd4:
	v_mfma_f32_16x16x32_bf16 v[36:39], v[120:123], v[104:107], v[36:39]
	v_mfma_f32_16x16x32_bf16 v[32:35], v[124:127], v[104:107], v[32:35]
	v_mfma_f32_16x16x32_bf16 v[28:31], v[112:115], v[100:103], v[28:31]
	v_mfma_f32_16x16x32_bf16 v[24:27], v[116:119], v[100:103], v[24:27]
	s_cmp_gt_u32 s61, 41
	s_cbranch_scc1 .Lgc5_skd5
	s_add_u32 m0, s98, 0xa000
	s_nop 0
	global_load_lds_dwordx4 v[172:173], off
.Lgc5_skd5:
	v_mfma_f32_16x16x32_bf16 v[20:23], v[120:123], v[100:103], v[20:23]
	v_mfma_f32_16x16x32_bf16 v[16:19], v[124:127], v[100:103], v[16:19]
	v_mfma_f32_16x16x32_bf16 v[12:15], v[112:115], v[96:99], v[12:15]
	v_mfma_f32_16x16x32_bf16 v[8:11], v[116:119], v[96:99], v[8:11]
	v_mfma_f32_16x16x32_bf16 v[4:7], v[120:123], v[96:99], v[4:7]
	v_mfma_f32_16x16x32_bf16 v[0:3], v[124:127], v[96:99], v[0:3]
	v_mfma_f32_16x16x32_bf16 v[60:63], v[80:83], v[76:79], v[60:63]
	v_mfma_f32_16x16x32_bf16 v[56:59], v[84:87], v[76:79], v[56:59]
	v_mfma_f32_16x16x32_bf16 v[52:55], v[88:91], v[76:79], v[52:55]
	v_mfma_f32_16x16x32_bf16 v[48:51], v[92:95], v[76:79], v[48:51]
	v_mfma_f32_16x16x32_bf16 v[44:47], v[80:83], v[72:75], v[44:47]
	v_mfma_f32_16x16x32_bf16 v[40:43], v[84:87], v[72:75], v[40:43]
	v_mfma_f32_16x16x32_bf16 v[36:39], v[88:91], v[72:75], v[36:39]
	v_mfma_f32_16x16x32_bf16 v[32:35], v[92:95], v[72:75], v[32:35]
	v_mfma_f32_16x16x32_bf16 v[28:31], v[80:83], v[68:71], v[28:31]
	v_mfma_f32_16x16x32_bf16 v[24:27], v[84:87], v[68:71], v[24:27]
	v_mfma_f32_16x16x32_bf16 v[20:23], v[88:91], v[68:71], v[20:23]
	v_mfma_f32_16x16x32_bf16 v[16:19], v[92:95], v[68:71], v[16:19]
	v_mfma_f32_16x16x32_bf16 v[12:15], v[80:83], v[64:67], v[12:15]
	v_mfma_f32_16x16x32_bf16 v[8:11], v[84:87], v[64:67], v[8:11]
	v_mfma_f32_16x16x32_bf16 v[4:7], v[88:91], v[64:67], v[4:7]
	v_mfma_f32_16x16x32_bf16 v[0:3], v[92:95], v[64:67], v[0:3]
	s_setprio 0
	s_add_i32 s36, s60, 1
	s_cmp_lg_u32 s60, 2
	s_cselect_b32 s60, s36, 0
	s_add_i32 s61, s61, 1
	s_add_u32 s10, s10, 0x80
	s_addc_u32 s11, s11, 0
	s_mul_i32 s36, s60, 0xc000
	v_add_u32_e32 v160, s36, v174
	v_add_u32_e32 v161, s36, v131
	s_mul_i32 s36, s60, 0x6000
	s_addk_i32 s36, 0xa000
	s_cmp_lg_u32 s60, 0
	s_cselect_b32 s36, s36, 0xc000
	s_lshl_b32 s36, s36, 1
	s_add_u32 s98, s36, s99
	v_lshl_add_u64 v[162:163], v[162:163], 0, s[14:15]
	v_lshl_add_u64 v[164:165], v[164:165], 0, s[14:15]
	v_lshl_add_u64 v[166:167], v[166:167], 0, s[14:15]
	v_lshl_add_u64 v[168:169], v[168:169], 0, s[14:15]
	v_lshl_add_u64 v[170:171], v[170:171], 0, s[14:15]
	v_lshl_add_u64 v[172:173], v[172:173], 0, s[14:15]
	s_barrier
	s_cmpk_eq_i32 s10, 0x1600
	s_cbranch_scc1 .LBB0_1062

; #define STAGE_ALL(bufi, kt) do { STAGEA(SA(bufi, 0), brow, kt); STAGEA(SA(bufi, 1), brow + HALF, kt); STAGEB(SB(bufi), bcol, kt); } while (0)
; #define WAIT_V(n) asm volatile("s_waitcnt vmcnt(" #n ")" ::: "memory")
; #define BAR __builtin_amdgcn_s_barrier()
;     ...
;     for (int t = 0; t < nt; ++t) {
;       const char* pa = (const char*)SA(b, wr >> 1);
;       const char* pb = (const char*)SB(b);
;       bf16x8 At[4][2], Bf[4][2];
; #pragma unroll
;       for (int m = 0; m < 4; ++m)
; #pragma unroll
;         for (int k = 0; k < 2; ++k) At[m][k] = *reinterpret_cast<const bf16x8*>(pa + lds_byte((wr & 1) * 64 + m * 16 + fr, k * 32 + fq * 8));
; #pragma unroll
;       for (int n = 0; n < 4; ++n)
; #pragma unroll
;         for (int k = 0; k < 2; ++k) Bf[n][k] = *reinterpret_cast<const bf16x8*>(pb + lds_byte(wc * 64 + n * 16 + fr, k * 32 + fq * 8));
;       if (t + 2 < nt) { const int b2 = (b == 0) ? 2 : b - 1; STAGE_ALL(b2, t + 2); WAIT_V(6); } else { WAIT_V(0); }
;       asm volatile("s_waitcnt lgkmcnt(0)" ::: "memory");
;       __builtin_amdgcn_sched_barrier(0);
;       BAR;
;       __builtin_amdgcn_sched_barrier(0);
;       __builtin_amdgcn_s_setprio(1);
; #pragma unroll
;       for (int k = 0; k < 2; ++k)
; #pragma unroll
;         for (int m = 0; m < 4; ++m)
; #pragma unroll
;           for (int n = 0; n < 4; ++n) acc[m][n] = __builtin_amdgcn_mfma_f32_16x16x32_bf16(Bf[n][k], At[m][k], acc[m][n], 0, 0, 0);
;       __builtin_amdgcn_s_setprio(0);
;       __builtin_amdgcn_sched_barrier(0);
;       BAR;
;       __builtin_amdgcn_sched_barrier(0);
;       b = (b == 2) ? 0 : b + 1;
;     }
.LBB0_1265:
	s_waitcnt lgkmcnt(0)
	s_barrier
	s_setprio 1
	s_waitcnt lgkmcnt(0)
	v_mfma_f32_16x16x32_bf16 v[56:59], v[112:115], v[108:111], v[56:59]
	v_mfma_f32_16x16x32_bf16 v[48:51], v[116:119], v[108:111], v[48:51]
	s_cmp_gt_u32 s58, 13
	s_cbranch_scc1 .Lgc6_skd3
	s_add_u32 m0, s98, 0x6000
	s_nop 0
	global_load_lds_dwordx4 v[168:169], off
.Lgc6_skd3:
	v_mfma_f32_16x16x32_bf16 v[60:63], v[120:123], v[108:111], v[60:63]
	v_mfma_f32_16x16x32_bf16 v[52:55], v[124:127], v[108:111], v[52:55]
	v_mfma_f32_16x16x32_bf16 v[40:43], v[112:115], v[104:107], v[40:43]
	v_mfma_f32_16x16x32_bf16 v[32:35], v[116:119], v[104:107], v[32:35]
	s_cmp_gt_u32 s58, 13
	s_cbranch_scc1 .Lgc6_skd4
	s_add_u32 m0, s98, 0x8000
	s_nop 0
	global_load_lds_dwordx4 v[170:171], off
.Lgc6_skd4:
	v_mfma_f32_16x16x32_bf16 v[44:47], v[120:123], v[104:107], v[44:47]
	v_mfma_f32_16x16x32_bf16 v[36:39], v[124:127], v[104:107], v[36:39]
	v_mfma_f32_16x16x32_bf16 v[24:27], v[112:115], v[100:103], v[24:27]
	v_mfma_f32_16x16x32_bf16 v[16:19], v[116:119], v[100:103], v[16:19]
	s_cmp_gt_u32 s58, 13
	s_cbranch_scc1 .Lgc6_skd5
	s_add_u32 m0, s98, 0xa000
	s_nop 0
	global_load_lds_dwordx4 v[172:173], off
.Lgc6_skd5:
	v_mfma_f32_16x16x32_bf16 v[28:31], v[120:123], v[100:103], v[28:31]
	v_mfma_f32_16x16x32_bf16 v[20:23], v[124:127], v[100:103], v[20:23]
	v_mfma_f32_16x16x32_bf16 v[8:11], v[112:115], v[96:99], v[8:11]
	v_mfma_f32_16x16x32_bf16 v[0:3], v[116:119], v[96:99], v[0:3]
	v_mfma_f32_16x16x32_bf16 v[12:15], v[120:123], v[96:99], v[12:15]
	v_mfma_f32_16x16x32_bf16 v[4:7], v[124:127], v[96:99], v[4:7]
	v_mfma_f32_16x16x32_bf16 v[56:59], v[80:83], v[76:79], v[56:59]
	v_mfma_f32_16x16x32_bf16 v[48:51], v[84:87], v[76:79], v[48:51]
	v_mfma_f32_16x16x32_bf16 v[60:63], v[88:91], v[76:79], v[60:63]
	v_mfma_f32_16x16x32_bf16 v[52:55], v[92:95], v[76:79], v[52:55]
	v_mfma_f32_16x16x32_bf16 v[40:43], v[80:83], v[72:75], v[40:43]
	v_mfma_f32_16x16x32_bf16 v[32:35], v[84:87], v[72:75], v[32:35]
	v_mfma_f32_16x16x32_bf16 v[44:47], v[88:91], v[72:75], v[44:47]
	v_mfma_f32_16x16x32_bf16 v[36:39], v[92:95], v[72:75], v[36:39]
	v_mfma_f32_16x16x32_bf16 v[24:27], v[80:83], v[68:71], v[24:27]
	v_mfma_f32_16x16x32_bf16 v[16:19], v[84:87], v[68:71], v[16:19]
	v_mfma_f32_16x16x32_bf16 v[28:31], v[88:91], v[68:71], v[28:31]
	v_mfma_f32_16x16x32_bf16 v[20:23], v[92:95], v[68:71], v[20:23]
	v_mfma_f32_16x16x32_bf16 v[8:11], v[80:83], v[64:67], v[8:11]
	v_mfma_f32_16x16x32_bf16 v[0:3], v[84:87], v[64:67], v[0:3]
	v_mfma_f32_16x16x32_bf16 v[12:15], v[88:91], v[64:67], v[12:15]
	v_mfma_f32_16x16x32_bf16 v[4:7], v[92:95], v[64:67], v[4:7]
	s_setprio 0
	s_add_i32 s36, s43, 1
	s_cmp_lg_u32 s43, 2
	s_cselect_b32 s43, s36, 0
	s_add_i32 s58, s58, 1
	s_add_u32 s10, s10, 0x80
	s_addc_u32 s11, s11, 0
	s_mul_i32 s36, s43, 0xc000
	v_add_u32_e32 v160, s36, v174
	v_add_u32_e32 v161, s36, v131
	s_mul_i32 s36, s43, 0x6000
	s_addk_i32 s36, 0xa000
	s_cmp_lg_u32 s43, 0
	s_cselect_b32 s36, s36, 0xc000
	s_lshl_b32 s36, s36, 1
	s_add_u32 s98, s36, s99
	v_lshl_add_u64 v[162:163], v[162:163], 0, s[14:15]
	v_lshl_add_u64 v[164:165], v[164:165], 0, s[14:15]
	v_lshl_add_u64 v[166:167], v[166:167], 0, s[14:15]
	v_lshl_add_u64 v[168:169], v[168:169], 0, s[14:15]
	v_lshl_add_u64 v[170:171], v[170:171], 0, s[14:15]
	v_lshl_add_u64 v[172:173], v[172:173], 0, s[14:15]
	s_barrier
	s_cmpk_eq_i32 s10, 0x800
	s_cbranch_scc1 .LBB0_1270
